# global attention: next tile first two K-fragment LDS reads hoisted right after the barrier
# baseline (speedup 1.0000x reference)
; DI void attn_item(const Params& p, int layer, int item, char* smem) {
;     ...
;   const int qpos = qpos0 + wid * 32 + l32;
;   bf16x8 qf[4];
; #pragma unroll
;   for (int s = 0; s < 4; ++s) qf[s] = *(const bf16x8*)(Qb + (size_t)qpos * 64 + s * 16 + h * 8);
;   f32x16 o0, o1;
; #pragma unroll
;   for (int r = 0; r < 16; ++r) { o0[r] = 0.f; o1[r] = 0.f; }
;   const int btype = (mode == 3) ? (hh < 6 ? 0 : (hh < 10 ? 1 : 2)) : (mode == 0 ? 2 : (mode == 1 ? 1 : 0));
;   float m_fix = p.bounds[layer * 8 + btype];
;   if (mode == 1) m_fix += p.bounds[layer * 8 + 4 + hh];
;   f32x16 cinit, lacc;
; #pragma unroll
;   for (int r = 0; r < 16; ++r) { cinit[r] = -m_fix; lacc[r] = 0.f; }
;   const bf16x8 ones = {(short)0x3F80, (short)0x3F80, (short)0x3F80, (short)0x3F80, (short)0x3F80, (short)0x3F80, (short)0x3F80, (short)0x3F80};
;   const int lr = tid >> 3, lc = tid & 7;
;   uint4 ka0, va0, kb0, vb0;
;     ...
;       const char* sK = smem + bufsel * KV_B;
;       const char* sV = sK + KT_B;
;       f32x16 S[2];
; #pragma unroll
;       for (int kt = 0; kt < 2; ++kt) {
; #pragma unroll
;         for (int s = 0; s < 4; ++s) {
;           bf16x8 kf = *(const bf16x8*)(sK + (kt * 32 + l32) * KROW + s * 32 + h * 16);
;           S[kt] = MFMA32(kf, qf[s], s == 0 ? cinit : S[kt]);
;         }
;       }
;       if (tile < 64 && maskmode == 1) {
;         int qr = tq >> 6, qc = tq & 63;
;         int ws = min(max(qc - 8, 0), 48);
;         int dr = tile - qr + 7;
; #pragma unroll
;         for (int kt = 0; kt < 2; ++kt)
; #pragma unroll
;           for (int r = 0; r < 16; ++r) {
;             int kc = kt * 32 + crow(r, h);
;             bool ok = (unsigned)(kc - ws) < 16u;
;             int bi = ok ? (dr * 31 + kc - qc + 15) : 0;
;             float bv = s_rpb[bi];
;             S[kt][r] = ok ? (S[kt][r] + bv) : -INFINITY;
;           }
;       } else if (tile < 64 && maskmode == 2) {
; #pragma unroll
;         for (int kt = 0; kt < 2; ++kt)
; #pragma unroll
;           for (int r = 0; r < 16; ++r) {
;             int tk = tile * 64 + kt * 32 + crow(r, h);
;             int dd = tq - tk;
;             bool ok = (dd <= 128) && (dd >= -128);
;             S[kt][r] = ok ? S[kt][r] : -INFINITY;
;           }
;       }
; #pragma unroll
;       for (int r = 0; r < 16; ++r) {
;         S[0][r] = __builtin_amdgcn_exp2f(S[0][r]);
;         S[1][r] = __builtin_amdgcn_exp2f(S[1][r]);
;       }
.LBB0_259:
	s_mul_hi_i32 s0, s14, 0x2aaaaaab
	s_lshr_b32 s1, s0, 31
	s_ashr_i32 s5, s0, 4
	s_add_i32 s5, s5, s1
	s_mul_i32 s0, s5, 0x60
	s_sub_i32 s0, s14, s0
	v_mov_b32_e32 v32, v213
	s_ashr_i32 s4, s0, 4
	s_lshl_b32 s0, s0, 8
	s_and_b32 s8, s0, 0xf00
	s_lshl_b32 s0, s5, 5
	v_ashrrev_i32_e32 v0, 1, v32
	s_add_i32 s1, s4, s0
	s_mul_i32 s2, s4, 0x56
	v_and_b32_e32 v0, 0xffffffe0, v0
	v_and_b32_e32 v36, 31, v32
	s_bfe_u32 s3, s2, 0x1000f
	s_bfe_u32 s2, s2, 0x80008
	s_add_i32 s1, s1, 22
	v_add_u32_e32 v0, s8, v0
	s_add_i32 s2, s2, s3
	s_mul_hi_i32 s3, s1, 0x88000
	s_mul_i32 s1, s1, 0x88000
	v_or_b32_e32 v134, v0, v36
	s_add_u32 s6, s88, s1
	v_ashrrev_i32_e32 v135, 31, v134
	v_bfe_u32 v140, v32, 5, 1
	s_addc_u32 s7, s89, s3
	v_lshlrev_b64 v[2:3], 7, v[134:135]
	v_lshl_add_u64 v[2:3], s[6:7], 0, v[2:3]
	v_lshlrev_b32_e32 v18, 4, v140
	v_mov_b32_e32 v19, v1
	v_readlane_b32 s6, v254, 50
	v_lshl_add_u64 v[2:3], v[2:3], 0, v[18:19]
	v_readlane_b32 s7, v254, 51
	global_load_dwordx4 v[98:101], v[2:3], off
	global_load_dwordx4 v[102:105], v[2:3], off offset:32
	global_load_dwordx4 v[106:109], v[2:3], off offset:64
	global_load_dwordx4 v[110:113], v[2:3], off offset:96
	s_sext_i32_i8 s2, s2
	global_load_dword v0, v1, s[6:7] offset:8
	s_add_i32 s2, s0, s2
	s_mul_i32 s3, s2, 0x88000
	s_add_i32 s0, s2, 28
	s_mul_hi_i32 s1, s0, 0x88000
	s_add_i32 s0, s3, 0xee0000
	v_ashrrev_i32_e32 v30, 3, v32
	s_add_u32 s0, s88, s0
	v_ashrrev_i32_e32 v31, 31, v30
	s_addc_u32 s1, s89, s1
	v_lshlrev_b32_e32 v19, 4, v32
	v_lshlrev_b64 v[20:21], 7, v[30:31]
	v_lshl_add_u64 v[136:137], s[0:1], 0, v[20:21]
	s_mov_b32 s6, 0x80000
	s_add_i32 s2, s2, 30
	s_add_i32 s3, s3, 0xff0000
	s_mul_hi_i32 s9, s2, 0x88000
	s_add_u32 s2, s88, s3
	s_addc_u32 s3, s89, s9
	v_mov_b64_e32 v[26:27], s[2:3]
	v_mad_i64_i32 v[138:139], s[2:3], v30, s28, v[26:27]
	s_movk_i32 s3, 0x90
	s_mov_b32 s2, 0x82000
	v_mul_lo_u32 v30, v30, s3
	v_add_u32_e32 v30, 16, v30
	v_add_u32_e32 v144, 16, v18
	v_mul_u32_u24_e32 v145, 0x90, v36
	v_mad_u32_u24 v146, v36, s3, v144
	s_waitcnt vmcnt(0)
	v_xor_b32_e32 v2, 0x80000000, v0
	v_and_b32_e32 v0, 0x70, v19
	v_lshl_add_u64 v[34:35], v[136:137], 0, v[0:1]
	v_add_co_u32_e32 v22, vcc, s6, v34
	v_add_u32_e32 v135, v30, v0
	s_nop 0
	v_addc_co_u32_e32 v23, vcc, 0, v35, vcc
	global_load_dwordx4 v[22:25], v[22:23], off
	v_add_co_u32_e32 v26, vcc, s2, v34
	v_lshl_add_u64 v[74:75], v[138:139], 0, v[0:1]
	s_nop 0
	v_addc_co_u32_e32 v27, vcc, 0, v35, vcc
	global_load_dwordx4 v[26:29], v[26:27], off
	s_movk_i32 s2, 0x2000
	v_mov_b32_e32 v3, v2
	v_mov_b32_e32 v4, v2
	v_mov_b32_e32 v5, v2
	v_mov_b32_e32 v6, v2
	v_mov_b32_e32 v7, v2
	v_mov_b32_e32 v8, v2
	v_mov_b32_e32 v9, v2
	v_mov_b32_e32 v10, v2
	v_mov_b32_e32 v11, v2
	v_mov_b32_e32 v12, v2
	v_mov_b32_e32 v13, v2
	v_mov_b32_e32 v14, v2
	v_mov_b32_e32 v15, v2
	v_mov_b32_e32 v16, v2
	v_mov_b32_e32 v17, v2
	s_waitcnt vmcnt(0)
	ds_write_b128 v135, v[22:25]
	v_lshlrev_b32_e32 v22, 3, v32
	v_and_b32_e32 v22, 8, v22
	v_and_or_b32 v19, v19, s74, v22
	v_add_co_u32_e32 v22, vcc, s2, v74
	v_add_u32_e32 v19, v30, v19
	s_nop 0
	v_addc_co_u32_e32 v23, vcc, 0, v75, vcc
	global_load_dwordx4 v[30:33], v[22:23], off
	s_mov_b32 s2, 0x84000
	v_add_co_u32_e32 v24, vcc, s2, v34
	v_add_u32_e32 v141, 0x2000, v19
	s_nop 0
	v_addc_co_u32_e32 v25, vcc, 0, v35, vcc
	global_load_dwordx4 v[66:69], v[24:25], off
	v_lshl_add_u64 v[24:25], s[0:1], 0, v[0:1]
	v_lshl_add_u64 v[76:77], v[24:25], 0, v[20:21]
	s_mov_b32 s0, 0x86000
	v_add_u32_e32 v143, 0x6800, v19
	s_waitcnt vmcnt(0)
	ds_write2_b64 v141, v[30:31], v[32:33] offset0:128 offset1:130
	v_mad_u32_u24 v30, v36, s3, 16
	v_add_u32_e32 v142, v30, v18
	global_load_dwordx4 v[70:73], v[22:23], off offset:256
	global_load_dwordx4 v[30:33], v[22:23], off offset:128
	v_add_co_u32_e32 v18, vcc, s0, v76
	s_waitcnt lgkmcnt(0)
	s_barrier
	ds_write_b128 v135, v[26:29] offset:18432
	v_addc_co_u32_e32 v19, vcc, 0, v77, vcc
	s_waitcnt vmcnt(0)
	ds_write2_b64 v143, v[30:31], v[32:33] offset0:128 offset1:130
	global_load_dwordx4 v[114:117], v[18:19], off
	global_load_dwordx4 v[118:121], v[22:23], off offset:384
	ds_read_b128 v[34:37], v146
	ds_read_b128 v[38:41], v146 offset:32
	v_mov_b64_e32 v[132:133], s[94:95]
	v_mov_b64_e32 v[130:131], s[92:93]
	s_waitcnt lgkmcnt(1)
	v_mfma_f32_32x32x16_bf16 v[18:33], v[34:37], v[98:101], v[2:17]
	ds_read_b128 v[34:37], v146 offset:64
	ds_read_b128 v[50:53], v146 offset:4608
	s_waitcnt lgkmcnt(2)
	v_mfma_f32_32x32x16_bf16 v[18:33], v[38:41], v[102:105], v[18:33]
	s_waitcnt lgkmcnt(1)
	v_mfma_f32_32x32x16_bf16 v[18:33], v[34:37], v[106:109], v[18:33]
	ds_read_b128 v[34:37], v146 offset:96
	s_waitcnt lgkmcnt(0)
	v_mfma_f32_32x32x16_bf16 v[18:33], v[34:37], v[110:113], v[18:33]
	v_mfma_f32_32x32x16_bf16 v[34:49], v[50:53], v[98:101], v[2:17]
	ds_read_b128 v[50:53], v146 offset:4640
	s_nop 9
	v_exp_f32_e32 v18, v18
	v_exp_f32_e32 v19, v19
	v_exp_f32_e32 v20, v20
	v_exp_f32_e32 v21, v21
	v_exp_f32_e32 v22, v22
	v_exp_f32_e32 v23, v23
	s_waitcnt lgkmcnt(0)
	v_mfma_f32_32x32x16_bf16 v[34:49], v[50:53], v[102:105], v[34:49]
	ds_read_b128 v[50:53], v146 offset:4672
	v_exp_f32_e32 v24, v24
	v_exp_f32_e32 v25, v25
	v_cvt_pk_bf16_f32 v18, v18, v19
	v_cvt_pk_bf16_f32 v19, v20, v21
	v_cvt_pk_bf16_f32 v20, v22, v23
	v_cvt_pk_bf16_f32 v21, v24, v25
	s_waitcnt lgkmcnt(0)
	v_mfma_f32_32x32x16_bf16 v[34:49], v[50:53], v[106:109], v[34:49]
	ds_read_b128 v[50:53], v146 offset:4704
	ds_read_b128 v[22:25], v142 offset:9216
	ds_read_b128 v[78:81], v142 offset:9248
	v_exp_f32_e32 v82, v26
	v_exp_f32_e32 v83, v27
	v_exp_f32_e32 v84, v28
	v_exp_f32_e32 v85, v29
	v_exp_f32_e32 v122, v30
	s_waitcnt lgkmcnt(2)
; DI void attn_item(const Params& p, int layer, int item, char* smem) {
;     ...
;       f32x16 S[2];
; #pragma unroll
;       for (int kt = 0; kt < 2; ++kt) {
; #pragma unroll
;         for (int s = 0; s < 4; ++s) {
;           bf16x8 kf = *(const bf16x8*)(sK + (kt * 32 + l32) * KROW + s * 32 + h * 16);
;           S[kt] = MFMA32(kf, qf[s], s == 0 ? cinit : S[kt]);
;         }
;       }
;       if (tile < 64 && maskmode == 1) {
;         int qr = tq >> 6, qc = tq & 63;
;         int ws = min(max(qc - 8, 0), 48);
;         int dr = tile - qr + 7;
; #pragma unroll
;         for (int kt = 0; kt < 2; ++kt)
; #pragma unroll
;           for (int r = 0; r < 16; ++r) {
;             int kc = kt * 32 + crow(r, h);
;             bool ok = (unsigned)(kc - ws) < 16u;
;             int bi = ok ? (dr * 31 + kc - qc + 15) : 0;
;             float bv = s_rpb[bi];
;             S[kt][r] = ok ? (S[kt][r] + bv) : -INFINITY;
;           }
;       } else if (tile < 64 && maskmode == 2) {
; #pragma unroll
;         for (int kt = 0; kt < 2; ++kt)
; #pragma unroll
;           for (int r = 0; r < 16; ++r) {
;             int tk = tile * 64 + kt * 32 + crow(r, h);
;             int dd = tq - tk;
;             bool ok = (dd <= 128) && (dd >= -128);
;             S[kt][r] = ok ? S[kt][r] : -INFINITY;
;           }
;       }
; #pragma unroll
;       for (int r = 0; r < 16; ++r) {
;         S[0][r] = __builtin_amdgcn_exp2f(S[0][r]);
;         S[1][r] = __builtin_amdgcn_exp2f(S[1][r]);
;       }
; #pragma unroll
;       for (int kt = 0; kt < 2; ++kt)
; #pragma unroll
;         for (int s2 = 0; s2 < 2; ++s2) {
;           uint4 pw;
;           pw.x = pack_bf16(S[kt][8 * s2 + 0], S[kt][8 * s2 + 1]);
;           pw.y = pack_bf16(S[kt][8 * s2 + 2], S[kt][8 * s2 + 3]);
;           pw.z = pack_bf16(S[kt][8 * s2 + 4], S[kt][8 * s2 + 5]);
;           pw.w = pack_bf16(S[kt][8 * s2 + 6], S[kt][8 * s2 + 7]);
;           bf16x8 pf = __builtin_bit_cast(bf16x8, pw);
;           const int koff = (kt * 32 + 16 * s2 + 8 * h) * 2;
;           {
;             bf16x8 vf = *(const bf16x8*)(sV + l32 * VROW + koff);
;             o0 = MFMA32(vf, pf, o0);
;             lacc = MFMA32(ones, pf, lacc);
;           }
;           {
;             bf16x8 vf = *(const bf16x8*)(sV + (32 + l32) * VROW + koff);
;             o1 = MFMA32(vf, pf, o1);
;           }
;         }
;     ...
;   for (int it = 0; it < n_it; it += 2) {
	v_mfma_f32_32x32x16_bf16 v[34:49], v[50:53], v[110:113], v[34:49]
	v_exp_f32_e32 v124, v31
	v_exp_f32_e32 v126, v32
	v_exp_f32_e32 v128, v33
	v_cvt_pk_bf16_f32 v82, v82, v83
	v_cvt_pk_bf16_f32 v83, v84, v85
	v_cvt_pk_bf16_f32 v84, v122, v124
	v_cvt_pk_bf16_f32 v85, v126, v128
	s_nop 4
	v_exp_f32_e32 v86, v34
	v_exp_f32_e32 v87, v35
	v_exp_f32_e32 v88, v36
	v_exp_f32_e32 v89, v37
	v_exp_f32_e32 v90, v38
	v_exp_f32_e32 v91, v39
	v_exp_f32_e32 v92, v40
	v_exp_f32_e32 v93, v41
	v_exp_f32_e32 v94, v42
	v_exp_f32_e32 v95, v43
	v_exp_f32_e32 v96, v44
	v_exp_f32_e32 v97, v45
	v_exp_f32_e32 v123, v46
	v_exp_f32_e32 v125, v47
	v_exp_f32_e32 v127, v48
	v_exp_f32_e32 v129, v49
	s_waitcnt lgkmcnt(1)
	v_mfma_f32_32x32x16_bf16 v[34:49], v[22:25], v[18:21], 0
	ds_read_b128 v[22:25], v142 offset:13824
	s_waitcnt lgkmcnt(1)
	v_mfma_f32_32x32x16_bf16 v[34:49], v[78:81], v[82:85], v[34:49]
	ds_read_b128 v[78:81], v142 offset:13856
	v_mfma_f32_32x32x16_bf16 v[50:65], v[130:133], v[18:21], 0
	s_waitcnt lgkmcnt(1)
	v_mfma_f32_32x32x16_bf16 v[18:33], v[22:25], v[18:21], 0
	v_mfma_f32_32x32x16_bf16 v[50:65], v[130:133], v[82:85], v[50:65]
	s_waitcnt lgkmcnt(0)
	v_mfma_f32_32x32x16_bf16 v[18:33], v[78:81], v[82:85], v[18:33]
	ds_read_b128 v[82:85], v142 offset:9280
	v_cvt_pk_bf16_f32 v78, v86, v87
	v_cvt_pk_bf16_f32 v79, v88, v89
	v_cvt_pk_bf16_f32 v80, v90, v91
	v_cvt_pk_bf16_f32 v81, v92, v93
	s_waitcnt lgkmcnt(0)
	s_nop 0
	v_mfma_f32_32x32x16_bf16 v[34:49], v[82:85], v[78:81], v[34:49]
	ds_read_b128 v[82:85], v142 offset:13888
	s_waitcnt lgkmcnt(0)
	v_mfma_f32_32x32x16_bf16 v[18:33], v[82:85], v[78:81], v[18:33]
	ds_read_b128 v[82:85], v142 offset:9312
	v_mfma_f32_32x32x16_bf16 v[50:65], v[130:133], v[78:81], v[50:65]
	v_cvt_pk_bf16_f32 v78, v94, v95
	v_cvt_pk_bf16_f32 v79, v96, v97
	v_cvt_pk_bf16_f32 v80, v123, v125
	v_cvt_pk_bf16_f32 v81, v127, v129
	s_waitcnt lgkmcnt(0)
	s_nop 0
	v_mfma_f32_32x32x16_bf16 v[34:49], v[82:85], v[78:81], v[34:49]
	ds_read_b128 v[82:85], v142 offset:13920
	s_waitcnt lgkmcnt(0)
	s_barrier
	ds_write_b128 v135, v[66:69]
	ds_write2_b64 v141, v[70:71], v[72:73] offset0:128 offset1:130
	global_load_dwordx4 v[122:125], v[76:77], off
	global_load_dwordx4 v[126:129], v[74:75], off
	v_mfma_f32_32x32x16_bf16 v[50:65], v[130:133], v[78:81], v[50:65]
	v_mfma_f32_32x32x16_bf16 v[18:33], v[82:85], v[78:81], v[18:33]
	ds_read_b128 v[82:85], v146 offset:18432
	ds_read_b128 v[86:89], v146 offset:18464
	s_mov_b32 s2, 2
	v_add_u32_e32 v144, v144, v145
	s_waitcnt lgkmcnt(1)
	v_mfma_f32_32x32x16_bf16 v[66:81], v[82:85], v[98:101], v[2:17]
	ds_read_b128 v[82:85], v146 offset:18496
	ds_read_b128 v[148:151], v146 offset:23040
	s_waitcnt lgkmcnt(2)
	v_mfma_f32_32x32x16_bf16 v[66:81], v[86:89], v[102:105], v[66:81]
	s_waitcnt lgkmcnt(1)
	v_mfma_f32_32x32x16_bf16 v[66:81], v[82:85], v[106:109], v[66:81]
	ds_read_b128 v[82:85], v146 offset:18528
	s_waitcnt lgkmcnt(0)
	v_mfma_f32_32x32x16_bf16 v[66:81], v[82:85], v[110:113], v[66:81]
	v_mfma_f32_32x32x16_bf16 v[82:97], v[148:151], v[98:101], v[2:17]
	ds_read_b128 v[148:151], v146 offset:23072
	s_nop 9
	v_exp_f32_e32 v66, v66
	v_exp_f32_e32 v67, v67
	v_exp_f32_e32 v68, v68
	v_exp_f32_e32 v69, v69
	v_exp_f32_e32 v70, v70
	v_exp_f32_e32 v71, v71
	s_waitcnt lgkmcnt(0)
	v_mfma_f32_32x32x16_bf16 v[82:97], v[148:151], v[102:105], v[82:97]
	ds_read_b128 v[148:151], v146 offset:23104
	v_exp_f32_e32 v72, v72
	v_exp_f32_e32 v73, v73
	v_cvt_pk_bf16_f32 v66, v66, v67
	v_cvt_pk_bf16_f32 v67, v68, v69
	v_cvt_pk_bf16_f32 v68, v70, v71
	v_cvt_pk_bf16_f32 v69, v72, v73
	s_waitcnt lgkmcnt(0)
	v_mfma_f32_32x32x16_bf16 v[82:97], v[148:151], v[106:109], v[82:97]
	ds_read_b128 v[146:149], v146 offset:23136
	v_exp_f32_e32 v78, v78
	v_exp_f32_e32 v79, v79
	v_exp_f32_e32 v80, v80
	v_exp_f32_e32 v81, v81
	s_waitcnt lgkmcnt(0)
	v_mfma_f32_32x32x16_bf16 v[82:97], v[146:149], v[110:113], v[82:97]
	v_exp_f32_e32 v146, v74
	v_exp_f32_e32 v147, v75
	v_exp_f32_e32 v148, v76
	v_exp_f32_e32 v149, v77
	ds_read_b128 v[70:73], v142 offset:27648
	ds_read_b128 v[74:77], v142 offset:27680
	s_nop 5
	v_exp_f32_e32 v82, v82
	s_waitcnt lgkmcnt(1)
	v_mfma_f32_32x32x16_bf16 v[34:49], v[70:73], v[66:69], v[34:49]
	ds_read_b128 v[70:73], v142 offset:32256
	v_exp_f32_e32 v83, v83
	v_exp_f32_e32 v84, v84
	v_exp_f32_e32 v85, v85
	v_exp_f32_e32 v86, v86
	v_exp_f32_e32 v87, v87
	v_exp_f32_e32 v88, v88
	s_waitcnt lgkmcnt(0)
	v_mfma_f32_32x32x16_bf16 v[18:33], v[70:73], v[66:69], v[18:33]
	ds_read_b128 v[70:73], v142 offset:32288
	v_exp_f32_e32 v89, v89
	v_exp_f32_e32 v90, v90
	v_exp_f32_e32 v91, v91
	v_exp_f32_e32 v92, v92
	v_exp_f32_e32 v93, v93
	v_exp_f32_e32 v94, v94
	v_mfma_f32_32x32x16_bf16 v[50:65], v[130:133], v[66:69], v[50:65]
	v_cvt_pk_bf16_f32 v66, v146, v147
	v_cvt_pk_bf16_f32 v67, v148, v149
	v_cvt_pk_bf16_f32 v68, v78, v79
	v_cvt_pk_bf16_f32 v69, v80, v81
	v_exp_f32_e32 v95, v95
	v_exp_f32_e32 v96, v96
	v_exp_f32_e32 v97, v97
	s_waitcnt lgkmcnt(0)
	v_mfma_f32_32x32x16_bf16 v[18:33], v[70:73], v[66:69], v[18:33]
	ds_read_b128 v[70:73], v142 offset:27712
	v_mfma_f32_32x32x16_bf16 v[34:49], v[74:77], v[66:69], v[34:49]
	v_mfma_f32_32x32x16_bf16 v[50:65], v[130:133], v[66:69], v[50:65]
	v_cvt_pk_bf16_f32 v66, v82, v83
	v_cvt_pk_bf16_f32 v67, v84, v85
	v_cvt_pk_bf16_f32 v68, v86, v87
	v_cvt_pk_bf16_f32 v69, v88, v89
	s_waitcnt lgkmcnt(0)
	s_nop 0
	v_mfma_f32_32x32x16_bf16 v[34:49], v[70:73], v[66:69], v[34:49]
	ds_read_b128 v[70:73], v142 offset:32320
	s_waitcnt lgkmcnt(0)
	v_mfma_f32_32x32x16_bf16 v[18:33], v[70:73], v[66:69], v[18:33]
	ds_read_b128 v[70:73], v142 offset:27744
	v_mfma_f32_32x32x16_bf16 v[50:65], v[130:133], v[66:69], v[50:65]
	v_cvt_pk_bf16_f32 v66, v90, v91
	v_cvt_pk_bf16_f32 v67, v92, v93
	v_cvt_pk_bf16_f32 v68, v94, v95
	v_cvt_pk_bf16_f32 v69, v96, v97
	s_waitcnt lgkmcnt(0)
	s_nop 0
	v_mfma_f32_32x32x16_bf16 v[34:49], v[70:73], v[66:69], v[34:49]
	ds_read_b128 v[70:73], v142 offset:32352
	s_waitcnt lgkmcnt(0)
	s_barrier
	ds_read_b128 v[82:85], v144
	ds_read_b128 v[86:89], v144 offset:32
	v_mfma_f32_32x32x16_bf16 v[50:65], v[130:133], v[66:69], v[50:65]
	v_mfma_f32_32x32x16_bf16 v[18:33], v[70:73], v[66:69], v[18:33]
	s_nop 11
	v_mov_b32_e32 v51, 0
	v_mov_b32_e32 v52, 0
	s_branch .LBB0_261
; DI void attn_item(const Params& p, int layer, int item, char* smem) {
;     ...
;       f32x16 S[2];
; #pragma unroll
;       for (int kt = 0; kt < 2; ++kt) {
; #pragma unroll
;         for (int s = 0; s < 4; ++s) {
;           bf16x8 kf = *(const bf16x8*)(sK + (kt * 32 + l32) * KROW + s * 32 + h * 16);
;           S[kt] = MFMA32(kf, qf[s], s == 0 ? cinit : S[kt]);
;         }
;       }
;       if (tile < 64 && maskmode == 1) {
;         int qr = tq >> 6, qc = tq & 63;
;         int ws = min(max(qc - 8, 0), 48);
;         int dr = tile - qr + 7;
; #pragma unroll
;         for (int kt = 0; kt < 2; ++kt)
; #pragma unroll
;           for (int r = 0; r < 16; ++r) {
;             int kc = kt * 32 + crow(r, h);
;             bool ok = (unsigned)(kc - ws) < 16u;
;             int bi = ok ? (dr * 31 + kc - qc + 15) : 0;
;             float bv = s_rpb[bi];
;             S[kt][r] = ok ? (S[kt][r] + bv) : -INFINITY;
;           }
;       } else if (tile < 64 && maskmode == 2) {
; #pragma unroll
;         for (int kt = 0; kt < 2; ++kt)
; #pragma unroll
;           for (int r = 0; r < 16; ++r) {
;             int tk = tile * 64 + kt * 32 + crow(r, h);
;             int dd = tq - tk;
;             bool ok = (dd <= 128) && (dd >= -128);
;             S[kt][r] = ok ? S[kt][r] : -INFINITY;
;           }
;       }
; #pragma unroll
;       for (int r = 0; r < 16; ++r) {
;         S[0][r] = __builtin_amdgcn_exp2f(S[0][r]);
;         S[1][r] = __builtin_amdgcn_exp2f(S[1][r]);
;       }
; #pragma unroll
;       for (int kt = 0; kt < 2; ++kt)
; #pragma unroll
;         for (int s2 = 0; s2 < 2; ++s2) {
;           uint4 pw;
;           pw.x = pack_bf16(S[kt][8 * s2 + 0], S[kt][8 * s2 + 1]);
;           pw.y = pack_bf16(S[kt][8 * s2 + 2], S[kt][8 * s2 + 3]);
;           pw.z = pack_bf16(S[kt][8 * s2 + 4], S[kt][8 * s2 + 5]);
;           pw.w = pack_bf16(S[kt][8 * s2 + 6], S[kt][8 * s2 + 7]);
;           bf16x8 pf = __builtin_bit_cast(bf16x8, pw);
;           const int koff = (kt * 32 + 16 * s2 + 8 * h) * 2;
;           {
;             bf16x8 vf = *(const bf16x8*)(sV + l32 * VROW + koff);
;             o0 = MFMA32(vf, pf, o0);
;             lacc = MFMA32(ones, pf, lacc);
;           }
;           {
;             bf16x8 vf = *(const bf16x8*)(sV + (32 + l32) * VROW + koff);
;             o1 = MFMA32(vf, pf, o1);
;           }
;         }
;     ...
;     if (it + 1 < n_it) {
.LBB0_260:
	s_mov_b64 s[6:7], 0x100
	s_add_i32 s2, s2, 2
	v_lshl_add_u64 v[138:139], v[138:139], 0, s[6:7]
	s_waitcnt lgkmcnt(0)
	v_mfma_f32_32x32x16_bf16 v[66:81], v[82:85], v[98:101], v[2:17]
	ds_read_b128 v[82:85], v144 offset:18496
	ds_read_b128 v[130:133], v144 offset:23040
	v_lshl_add_u64 v[136:137], v[136:137], 0, s[96:97]
	s_andn2_b64 vcc, exec, s[0:1]
	s_waitcnt lgkmcnt(2)
	v_mfma_f32_32x32x16_bf16 v[66:81], v[86:89], v[102:105], v[66:81]
	s_waitcnt lgkmcnt(1)
	v_mfma_f32_32x32x16_bf16 v[66:81], v[82:85], v[106:109], v[66:81]
	ds_read_b128 v[82:85], v144 offset:18528
	s_waitcnt lgkmcnt(0)
	v_mfma_f32_32x32x16_bf16 v[66:81], v[82:85], v[110:113], v[66:81]
	v_mfma_f32_32x32x16_bf16 v[82:97], v[130:133], v[98:101], v[2:17]
	ds_read_b128 v[130:133], v144 offset:23072
	s_nop 9
	v_exp_f32_e32 v66, v66
	v_exp_f32_e32 v67, v67
	v_exp_f32_e32 v68, v68
	v_exp_f32_e32 v69, v69
	v_exp_f32_e32 v70, v70
	v_exp_f32_e32 v71, v71
	s_waitcnt lgkmcnt(0)
	v_mfma_f32_32x32x16_bf16 v[82:97], v[130:133], v[102:105], v[82:97]
	ds_read_b128 v[130:133], v144 offset:23104
	v_exp_f32_e32 v72, v72
	v_exp_f32_e32 v73, v73
	v_add_f32_e32 v51, v51, v66
	v_add_f32_e32 v52, v52, v67
	v_add_f32_e32 v51, v51, v68
	v_add_f32_e32 v52, v52, v69
	v_cvt_pk_bf16_f32 v66, v66, v67
	v_cvt_pk_bf16_f32 v67, v68, v69
	s_waitcnt lgkmcnt(0)
	v_mfma_f32_32x32x16_bf16 v[82:97], v[130:133], v[106:109], v[82:97]
	ds_read_b128 v[130:133], v144 offset:23136
	v_add_f32_e32 v51, v51, v70
	v_add_f32_e32 v52, v52, v71
	v_cvt_pk_bf16_f32 v68, v70, v71
	v_add_f32_e32 v51, v51, v72
	v_add_f32_e32 v52, v52, v73
	v_cvt_pk_bf16_f32 v69, v72, v73
	v_exp_f32_e32 v145, v78
	v_exp_f32_e32 v146, v79
	s_waitcnt lgkmcnt(0)
	v_mfma_f32_32x32x16_bf16 v[82:97], v[130:133], v[110:113], v[82:97]
	v_exp_f32_e32 v147, v80
	v_exp_f32_e32 v148, v81
	v_exp_f32_e32 v130, v74
	v_exp_f32_e32 v131, v75
	v_exp_f32_e32 v132, v76
	v_exp_f32_e32 v133, v77
	ds_read_b128 v[70:73], v142 offset:27648
	ds_read_b128 v[74:77], v142 offset:27680
	ds_read_b128 v[78:81], v142 offset:32256
	v_add_f32_e32 v51, v51, v145
	v_add_f32_e32 v52, v52, v146
	v_add_f32_e32 v51, v51, v147
	v_add_f32_e32 v52, v52, v148
	v_exp_f32_e32 v82, v82
	s_waitcnt lgkmcnt(2)
	v_mfma_f32_32x32x16_bf16 v[34:49], v[70:73], v[66:69], v[34:49]
	v_exp_f32_e32 v83, v83
	v_exp_f32_e32 v84, v84
	v_exp_f32_e32 v85, v85
	v_add_f32_e32 v51, v51, v130
	v_add_f32_e32 v52, v52, v131
	v_add_f32_e32 v51, v51, v132
	v_add_f32_e32 v52, v52, v133
	v_exp_f32_e32 v86, v86
	v_exp_f32_e32 v87, v87
	v_exp_f32_e32 v88, v88
	v_exp_f32_e32 v89, v89
	s_waitcnt lgkmcnt(0)
	v_mfma_f32_32x32x16_bf16 v[18:33], v[78:81], v[66:69], v[18:33]
	v_cvt_pk_bf16_f32 v66, v130, v131
	v_cvt_pk_bf16_f32 v67, v132, v133
	v_cvt_pk_bf16_f32 v68, v145, v146
	v_cvt_pk_bf16_f32 v69, v147, v148
	v_exp_f32_e32 v90, v90
	v_exp_f32_e32 v91, v91
	v_exp_f32_e32 v92, v92
	v_mfma_f32_32x32x16_bf16 v[34:49], v[74:77], v[66:69], v[34:49]
	ds_read_b128 v[74:77], v142 offset:32288
	v_exp_f32_e32 v93, v93
	v_exp_f32_e32 v94, v94
	v_exp_f32_e32 v95, v95
	v_exp_f32_e32 v96, v96
	v_exp_f32_e32 v97, v97
	v_add_f32_e32 v51, v51, v82
	v_add_f32_e32 v52, v52, v83
	s_waitcnt lgkmcnt(0)
	v_mfma_f32_32x32x16_bf16 v[18:33], v[74:77], v[66:69], v[18:33]
	ds_read_b128 v[74:77], v142 offset:27712
	v_add_f32_e32 v51, v51, v84
	v_add_f32_e32 v52, v52, v85
	v_add_f32_e32 v51, v51, v86
	v_add_f32_e32 v52, v52, v87
	v_cvt_pk_bf16_f32 v66, v82, v83
	v_cvt_pk_bf16_f32 v67, v84, v85
	v_cvt_pk_bf16_f32 v68, v86, v87
	v_cvt_pk_bf16_f32 v69, v88, v89
	s_waitcnt lgkmcnt(0)
	s_nop 0
	v_mfma_f32_32x32x16_bf16 v[34:49], v[74:77], v[66:69], v[34:49]
	ds_read_b128 v[74:77], v142 offset:32320
	v_add_f32_e32 v51, v51, v88
	v_add_f32_e32 v52, v52, v89
	v_add_f32_e32 v51, v51, v90
	v_add_f32_e32 v52, v52, v91
	s_waitcnt lgkmcnt(0)
	v_mfma_f32_32x32x16_bf16 v[18:33], v[74:77], v[66:69], v[18:33]
	v_cvt_pk_bf16_f32 v66, v90, v91
	v_cvt_pk_bf16_f32 v67, v92, v93
	v_cvt_pk_bf16_f32 v68, v94, v95
	v_cvt_pk_bf16_f32 v69, v96, v97
	ds_read_b128 v[74:77], v142 offset:27744
	ds_read_b128 v[70:73], v142 offset:32352
	v_add_f32_e32 v51, v51, v92
	v_add_f32_e32 v52, v52, v93
	v_add_f32_e32 v51, v51, v94
	v_add_f32_e32 v52, v52, v95
	v_add_f32_e32 v51, v51, v96
	v_add_f32_e32 v52, v52, v97
	s_waitcnt lgkmcnt(0)
	s_barrier
	ds_read_b128 v[82:85], v144
	ds_read_b128 v[86:89], v144 offset:32
	v_mfma_f32_32x32x16_bf16 v[34:49], v[74:77], v[66:69], v[34:49]
	v_mfma_f32_32x32x16_bf16 v[18:33], v[70:73], v[66:69], v[18:33]
	s_cbranch_vccz .LBB0_267

; DI void attn_item(const Params& p, int layer, int item, char* smem) {
;     ...
;       f32x16 S[2];
; #pragma unroll
;       for (int kt = 0; kt < 2; ++kt) {
; #pragma unroll
;         for (int s = 0; s < 4; ++s) {
;           bf16x8 kf = *(const bf16x8*)(sK + (kt * 32 + l32) * KROW + s * 32 + h * 16);
;           S[kt] = MFMA32(kf, qf[s], s == 0 ? cinit : S[kt]);
;         }
;       }
;       if (tile < 64 && maskmode == 1) {
;         int qr = tq >> 6, qc = tq & 63;
;         int ws = min(max(qc - 8, 0), 48);
;         int dr = tile - qr + 7;
; #pragma unroll
;         for (int kt = 0; kt < 2; ++kt)
; #pragma unroll
;           for (int r = 0; r < 16; ++r) {
;             int kc = kt * 32 + crow(r, h);
;             bool ok = (unsigned)(kc - ws) < 16u;
;             int bi = ok ? (dr * 31 + kc - qc + 15) : 0;
;             float bv = s_rpb[bi];
;             S[kt][r] = ok ? (S[kt][r] + bv) : -INFINITY;
;           }
;       } else if (tile < 64 && maskmode == 2) {
; #pragma unroll
;         for (int kt = 0; kt < 2; ++kt)
; #pragma unroll
;           for (int r = 0; r < 16; ++r) {
;             int tk = tile * 64 + kt * 32 + crow(r, h);
;             int dd = tq - tk;
;             bool ok = (dd <= 128) && (dd >= -128);
;             S[kt][r] = ok ? S[kt][r] : -INFINITY;
;           }
;       }
; #pragma unroll
;       for (int r = 0; r < 16; ++r) {
;         S[0][r] = __builtin_amdgcn_exp2f(S[0][r]);
;         S[1][r] = __builtin_amdgcn_exp2f(S[1][r]);
;       }
; #pragma unroll
;       for (int kt = 0; kt < 2; ++kt)
; #pragma unroll
;         for (int s2 = 0; s2 < 2; ++s2) {
;           uint4 pw;
;           pw.x = pack_bf16(S[kt][8 * s2 + 0], S[kt][8 * s2 + 1]);
;           pw.y = pack_bf16(S[kt][8 * s2 + 2], S[kt][8 * s2 + 3]);
;           pw.z = pack_bf16(S[kt][8 * s2 + 4], S[kt][8 * s2 + 5]);
;           pw.w = pack_bf16(S[kt][8 * s2 + 6], S[kt][8 * s2 + 7]);
;           bf16x8 pf = __builtin_bit_cast(bf16x8, pw);
;           const int koff = (kt * 32 + 16 * s2 + 8 * h) * 2;
;           {
;             bf16x8 vf = *(const bf16x8*)(sV + l32 * VROW + koff);
;             o0 = MFMA32(vf, pf, o0);
;             lacc = MFMA32(ones, pf, lacc);
;           }
;           {
;             bf16x8 vf = *(const bf16x8*)(sV + (32 + l32) * VROW + koff);
;             o1 = MFMA32(vf, pf, o1);
;           }
;         }
;     ...
;   for (int it = 0; it < n_it; it += 2) {
.LBB0_263:
	s_cmpk_gt_u32 s2, 0x41
	s_cselect_b64 s[0:1], -1, 0
	s_and_b64 vcc, exec, s[0:1]
	s_waitcnt lgkmcnt(0)
	v_mfma_f32_32x32x16_bf16 v[66:81], v[82:85], v[98:101], v[2:17]
	ds_read_b128 v[82:85], v144 offset:64
	ds_read_b128 v[146:149], v144 offset:4608
	s_waitcnt lgkmcnt(2)
	v_mfma_f32_32x32x16_bf16 v[66:81], v[86:89], v[102:105], v[66:81]
	s_waitcnt lgkmcnt(1)
	v_mfma_f32_32x32x16_bf16 v[66:81], v[82:85], v[106:109], v[66:81]
	ds_read_b128 v[82:85], v144 offset:96
	s_waitcnt lgkmcnt(0)
	v_mfma_f32_32x32x16_bf16 v[66:81], v[82:85], v[110:113], v[66:81]
	v_mfma_f32_32x32x16_bf16 v[82:97], v[146:149], v[98:101], v[2:17]
	ds_read_b128 v[146:149], v144 offset:4640
	s_nop 9
	v_exp_f32_e32 v66, v66
	v_exp_f32_e32 v67, v67
	v_exp_f32_e32 v68, v68
	v_exp_f32_e32 v69, v69
	v_exp_f32_e32 v70, v70
	v_exp_f32_e32 v71, v71
	s_waitcnt lgkmcnt(0)
	v_mfma_f32_32x32x16_bf16 v[82:97], v[146:149], v[102:105], v[82:97]
	ds_read_b128 v[146:149], v144 offset:4672
	v_exp_f32_e32 v72, v72
	v_exp_f32_e32 v73, v73
	v_exp_f32_e32 v145, v74
	v_add_f32_e32 v51, v51, v66
	v_add_f32_e32 v52, v52, v67
	v_add_f32_e32 v51, v51, v68
	v_add_f32_e32 v52, v52, v69
	v_cvt_pk_bf16_f32 v66, v66, v67
	v_cvt_pk_bf16_f32 v67, v68, v69
	s_waitcnt lgkmcnt(0)
	v_mfma_f32_32x32x16_bf16 v[82:97], v[146:149], v[106:109], v[82:97]
	ds_read_b128 v[146:149], v144 offset:4704
	v_add_f32_e32 v51, v51, v70
	v_add_f32_e32 v52, v52, v71
	v_cvt_pk_bf16_f32 v68, v70, v71
	v_add_f32_e32 v51, v51, v72
	v_add_f32_e32 v52, v52, v73
	v_cvt_pk_bf16_f32 v69, v72, v73
	v_exp_f32_e32 v150, v79
	v_exp_f32_e32 v151, v80
	s_waitcnt lgkmcnt(0)
	v_mfma_f32_32x32x16_bf16 v[82:97], v[146:149], v[110:113], v[82:97]
	v_exp_f32_e32 v152, v81
	v_exp_f32_e32 v146, v75
	v_exp_f32_e32 v147, v76
	v_exp_f32_e32 v148, v77
	v_exp_f32_e32 v149, v78
	ds_read_b128 v[70:73], v142 offset:9216
	ds_read_b128 v[74:77], v142 offset:9248
	ds_read_b128 v[78:81], v142 offset:13824
	v_add_f32_e32 v51, v51, v145
	v_add_f32_e32 v52, v52, v150
	v_add_f32_e32 v51, v51, v151
	v_add_f32_e32 v52, v52, v152
	v_exp_f32_e32 v82, v82
	s_waitcnt lgkmcnt(2)
	v_mfma_f32_32x32x16_bf16 v[34:49], v[70:73], v[66:69], v[34:49]
	v_exp_f32_e32 v83, v83
	v_exp_f32_e32 v84, v84
	v_exp_f32_e32 v85, v85
	v_add_f32_e32 v51, v51, v146
	v_add_f32_e32 v52, v52, v147
	v_add_f32_e32 v51, v51, v148
	v_add_f32_e32 v52, v52, v149
	v_exp_f32_e32 v86, v86
	v_exp_f32_e32 v87, v87
	v_exp_f32_e32 v88, v88
	v_exp_f32_e32 v89, v89
	s_waitcnt lgkmcnt(0)
	v_mfma_f32_32x32x16_bf16 v[18:33], v[78:81], v[66:69], v[18:33]
	v_cvt_pk_bf16_f32 v66, v145, v146
	v_cvt_pk_bf16_f32 v67, v147, v148
	v_cvt_pk_bf16_f32 v68, v149, v150
	v_cvt_pk_bf16_f32 v69, v151, v152
	v_exp_f32_e32 v90, v90
	v_exp_f32_e32 v91, v91
	v_exp_f32_e32 v92, v92
	v_mfma_f32_32x32x16_bf16 v[34:49], v[74:77], v[66:69], v[34:49]
	ds_read_b128 v[74:77], v142 offset:13856
	v_exp_f32_e32 v93, v93
	v_exp_f32_e32 v94, v94
	v_exp_f32_e32 v95, v95
	v_exp_f32_e32 v96, v96
	v_exp_f32_e32 v97, v97
	v_add_f32_e32 v51, v51, v82
	v_add_f32_e32 v52, v52, v83
	s_waitcnt lgkmcnt(0)
	v_mfma_f32_32x32x16_bf16 v[18:33], v[74:77], v[66:69], v[18:33]
	ds_read_b128 v[74:77], v142 offset:9280
	v_add_f32_e32 v51, v51, v84
	v_add_f32_e32 v52, v52, v85
	v_add_f32_e32 v51, v51, v86
	v_add_f32_e32 v52, v52, v87
	v_cvt_pk_bf16_f32 v66, v82, v83
	v_cvt_pk_bf16_f32 v67, v84, v85
	v_cvt_pk_bf16_f32 v68, v86, v87
	v_cvt_pk_bf16_f32 v69, v88, v89
	s_waitcnt lgkmcnt(0)
	s_nop 0
	v_mfma_f32_32x32x16_bf16 v[34:49], v[74:77], v[66:69], v[34:49]
	ds_read_b128 v[74:77], v142 offset:13888
	v_add_f32_e32 v51, v51, v88
	v_add_f32_e32 v52, v52, v89
	v_add_f32_e32 v51, v51, v90
	v_add_f32_e32 v52, v52, v91
	s_waitcnt lgkmcnt(0)
	v_mfma_f32_32x32x16_bf16 v[18:33], v[74:77], v[66:69], v[18:33]
	v_cvt_pk_bf16_f32 v66, v90, v91
	v_cvt_pk_bf16_f32 v67, v92, v93
	v_cvt_pk_bf16_f32 v68, v94, v95
	v_cvt_pk_bf16_f32 v69, v96, v97
	ds_read_b128 v[74:77], v142 offset:9312
	ds_read_b128 v[70:73], v142 offset:13920
	v_add_f32_e32 v51, v51, v92
	v_add_f32_e32 v52, v52, v93
	v_add_f32_e32 v51, v51, v94
	v_add_f32_e32 v52, v52, v95
	v_add_f32_e32 v51, v51, v96
	v_add_f32_e32 v52, v52, v97
	s_waitcnt lgkmcnt(0)
	s_barrier
	ds_read_b128 v[82:85], v144 offset:18432
	ds_read_b128 v[86:89], v144 offset:18464
	v_mfma_f32_32x32x16_bf16 v[34:49], v[74:77], v[66:69], v[34:49]
	v_mfma_f32_32x32x16_bf16 v[18:33], v[70:73], v[66:69], v[18:33]
	s_cbranch_vccnz .LBB0_265
	s_waitcnt vmcnt(1)
	ds_write_b128 v135, v[122:125]
	s_waitcnt vmcnt(0)
	ds_write2_b64 v141, v[126:127], v[128:129] offset0:128 offset1:130

; DI void attn_item(const Params& p, int layer, int item, char* smem) {
;     ...
;   float l_tot = lacc[0];
;   if (hasSink) l_tot += __builtin_amdgcn_exp2f(sinkv * LOG2E - m_fix);
;   float inv = 1.f / l_tot;
;   int T = (mode == 3) ? (TLAT + b * 256 + (qpos - 4096)) : (b * 4096 + qpos);
;   u16* od = p.O + (size_t)T * LDK + head16 * 64;
; #pragma unroll
;   for (int g = 0; g < 4; ++g) {
;     int d0 = 8 * g + 4 * h;
;     *(uint2*)(od + d0) = make_uint2(pack_bf16(o0[4 * g] * inv, o0[4 * g + 1] * inv), pack_bf16(o0[4 * g + 2] * inv, o0[4 * g + 3] * inv));
;     *(uint2*)(od + 32 + d0) = make_uint2(pack_bf16(o1[4 * g] * inv, o1[4 * g + 1] * inv), pack_bf16(o1[4 * g + 2] * inv, o1[4 * g + 3] * inv));
;   }
.LBB0_267:
	s_waitcnt lgkmcnt(0)
	s_nop 5
	v_add_f32_e32 v51, v51, v52
	s_nop 0
	v_mov_b32_e32 v52, v51
	s_nop 1
	v_permlane32_swap_b32_e32 v51, v52
	s_nop 1
	v_add_f32_e32 v50, v50, v51
	v_add_f32_e32 v50, v50, v52
	v_div_scale_f32 v0, s[0:1], v50, v50, 1.0
	v_rcp_f32_e32 v3, v0
	v_lshl_add_u32 v2, s5, 12, v134
	s_lshl_b32 s0, s4, 6
	s_ashr_i32 s1, s0, 31
	v_fma_f32 v4, -v0, v3, 1.0
	v_fmac_f32_e32 v3, v4, v3
	v_div_scale_f32 v4, vcc, 1.0, v50, 1.0
	v_mul_f32_e32 v5, v4, v3
	v_fma_f32 v6, -v0, v5, v4
	v_fmac_f32_e32 v5, v6, v3
	v_fma_f32 v0, -v0, v5, v4
	v_div_fmas_f32 v0, v0, v3, v5
	v_ashrrev_i32_e32 v3, 31, v2
	v_lshlrev_b64 v[2:3], 11, v[2:3]
	v_div_fixup_f32 v4, v0, v50, 1.0
	v_lshl_add_u64 v[2:3], s[90:91], 0, v[2:3]
	v_lshl_add_u64 v[2:3], s[0:1], 1, v[2:3]
	v_pk_mul_f32 v[6:7], v[34:35], v[4:5] op_sel_hi:[1,0]
	v_pk_mul_f32 v[8:9], v[36:37], v[4:5] op_sel_hi:[1,0]
	v_lshlrev_b32_e32 v0, 3, v140
	v_cvt_pk_bf16_f32 v6, v6, v7
	v_cvt_pk_bf16_f32 v7, v8, v9
	v_lshl_add_u64 v[2:3], v[2:3], 0, v[0:1]
	global_store_dwordx2 v[2:3], v[6:7], off offset:1280
	v_pk_mul_f32 v[6:7], v[4:5], v[18:19] op_sel_hi:[0,1]
	v_pk_mul_f32 v[8:9], v[4:5], v[20:21] op_sel_hi:[0,1]
	v_cvt_pk_bf16_f32 v6, v6, v7
	v_cvt_pk_bf16_f32 v7, v8, v9
	global_store_dwordx2 v[2:3], v[6:7], off offset:1344
	v_pk_mul_f32 v[6:7], v[38:39], v[4:5] op_sel_hi:[1,0]
	v_pk_mul_f32 v[8:9], v[40:41], v[4:5] op_sel_hi:[1,0]
	v_cvt_pk_bf16_f32 v6, v6, v7
	v_cvt_pk_bf16_f32 v7, v8, v9
	global_store_dwordx2 v[2:3], v[6:7], off offset:1296
	v_pk_mul_f32 v[6:7], v[4:5], v[22:23] op_sel_hi:[0,1]
	v_pk_mul_f32 v[8:9], v[4:5], v[24:25] op_sel_hi:[0,1]
	v_cvt_pk_bf16_f32 v6, v6, v7
	v_cvt_pk_bf16_f32 v7, v8, v9
	global_store_dwordx2 v[2:3], v[6:7], off offset:1360
	v_pk_mul_f32 v[6:7], v[42:43], v[4:5] op_sel_hi:[1,0]
	v_pk_mul_f32 v[8:9], v[44:45], v[4:5] op_sel_hi:[1,0]
	v_cvt_pk_bf16_f32 v6, v6, v7
	v_cvt_pk_bf16_f32 v7, v8, v9
	global_store_dwordx2 v[2:3], v[6:7], off offset:1312
	v_pk_mul_f32 v[6:7], v[4:5], v[26:27] op_sel_hi:[0,1]
	v_pk_mul_f32 v[8:9], v[4:5], v[28:29] op_sel_hi:[0,1]
	v_cvt_pk_bf16_f32 v6, v6, v7
	v_cvt_pk_bf16_f32 v7, v8, v9
	global_store_dwordx2 v[2:3], v[6:7], off offset:1376
	v_pk_mul_f32 v[6:7], v[46:47], v[4:5] op_sel_hi:[1,0]
	v_pk_mul_f32 v[8:9], v[48:49], v[4:5] op_sel_hi:[1,0]
	v_cvt_pk_bf16_f32 v6, v6, v7
	v_cvt_pk_bf16_f32 v7, v8, v9
	global_store_dwordx2 v[2:3], v[6:7], off offset:1328
	v_pk_mul_f32 v[6:7], v[4:5], v[30:31] op_sel_hi:[0,1]
	v_pk_mul_f32 v[4:5], v[4:5], v[32:33] op_sel_hi:[0,1]
	v_cvt_pk_bf16_f32 v6, v6, v7
	v_cvt_pk_bf16_f32 v7, v4, v5
	global_store_dwordx2 v[2:3], v[6:7], off offset:1392
	s_and_saveexec_b64 s[0:1], s[68:69]
	s_cbranch_execz .LBB0_236
	s_branch .LBB0_498
